# diff-attn loop back edge rotated: loop-back barrier is the loop head, counter test and branch sit before it (exit path has its own barrier copy)
# baseline (speedup 1.0000x reference)
; #define SBAR() __builtin_amdgcn_sched_barrier(0)
; #define VMW() asm volatile("s_waitcnt vmcnt(0)" ::: "memory")
; #define SLOAD_H(Kp, Vp, k0) do { S.st_v0 = load8<TIn>(ROW(Vp, k0, sr)); S.st_v1 = load8<TIn>(ROW(Vp, k0, 32 + sr));              \
;                          S.st_k0 = load8<TIn>(ROW(Kp, k0, sr)); S.st_k1 = load8<TIn>(ROW(Kp, k0, 32 + sr)); } while (0)
; #define SWRITE_HV(bf) do { *(bf16x8*)(V_lds + (bf) * SHM_V + vst0) = S.st_v0; *(bf16x8*)(V_lds + (bf) * SHM_V + vst1) = S.st_v1; } while (0)
; #define SWRITE_H(bf) do { SWRITE_HV(bf); SWRITE_HK(bf); } while (0)
; #define ACT(t) (KBASE(t) <= qlo + QBLK - 1 && KBASE(t) + KVBLK - 1 >= qlo - W + 1)
; __device__ __forceinline__ void partialSM(f32x16& p0, f32x16& p1, float& m_reg, float& mn, float& alpha) {
;     float pmax = p0[0]; for (int r = 1; r < 16; ++r) pmax = fmaxf(pmax, p0[r]); for (int r = 0; r < 16; ++r) pmax = fmaxf(pmax, p1[r]);
;     { auto rr = __builtin_amdgcn_permlane32_swap(__float_as_uint(pmax), __float_as_uint(pmax), false, false);
;       pmax = fmaxf(__uint_as_float(rr[0]), __uint_as_float(rr[1])); }
;     constexpr float C2 = 1.4426950408889634f * SCALE;
;     if (__builtin_expect(__all((pmax - m_reg) * SCALE <= THR), 1)) { mn = m_reg; alpha = 1.f; }
;     else { mn = fmaxf(m_reg, pmax); alpha = __builtin_amdgcn_exp2f((m_reg - mn) * C2); m_reg = mn; }
;     const float mnL = -mn * C2;
;     for (int r = 0; r < 16; ++r) p0[r] = fmaf(p0[r], C2, mnL); for (int r = 0; r < 16; ++r) p1[r] = fmaf(p1[r], C2, mnL);
;     for (int r = 0; r < 16; ++r) p0[r] = __builtin_amdgcn_exp2f(p0[r]);
; template <class TIn, class TOut>
; __device__ __forceinline__ void causal_swa_block(const BlockRef<TIn, TOut>& cur, const BlockRef<TIn, TOut>& nxt, int skv, int W, char* lds, Seam<TIn>& S) {
;     ...
;     if constexpr (F32) { VMW(); SWRITE_VF(0); SBAR(); } else { SWRITE_HV(0); SBAR(); }
;     if (NT > 1) { if constexpr (F32) SLOAD_F((const float*)Kh, KBASE(1)); else SLOAD_H(Kh, Vh, KBASE(1)); }
;     SBAR(); qkt<0, SK>(pA0, pA1, K_lds, r32, hi, S.qr, ACT(0));
;     if constexpr (F32) { if (NT > 1) { VMW(); SWRITE_KF(1); SBAR(); SLOAD_F((const float*)Vh, KBASE(1)); } }
;     MASKT(pA0, pA1, 0); partialSM(pA0, pA1, m_reg, mnA, alA);
;     if (NT > 1) { VMW(); if constexpr (F32) { SWRITE_VF(1); SBAR(); if (NT > 2) SLOAD_F((const float*)Kh, KBASE(2)); } else SWRITE_H(1); }
;     __syncthreads();
.LBB0_1128:
	s_nop 8
	v_max_f32_e32 v50, v19, v19
	v_max_f32_e32 v51, v18, v18
	v_max_f32_e32 v50, v51, v50
	v_max3_f32 v50, v50, v20, v21
	v_max3_f32 v50, v50, v22, v23
	v_max3_f32 v50, v50, v24, v25
	v_max3_f32 v50, v50, v26, v27
	v_max3_f32 v50, v50, v28, v29
	v_max3_f32 v50, v50, v30, v31
	v_max3_f32 v50, v50, v32, v33
	v_max3_f32 v50, v50, v2, v3
	v_max3_f32 v50, v50, v4, v5
	v_max3_f32 v50, v50, v6, v7
	v_max3_f32 v50, v50, v8, v9
	v_max3_f32 v50, v50, v10, v11
	v_max3_f32 v50, v50, v12, v13
	v_max3_f32 v50, v50, v14, v15
	v_max3_f32 v50, v50, v16, v17
	v_mov_b32_e32 v51, v50
	s_nop 1
	v_permlane32_swap_b32_e32 v50, v51
	v_max_f32_e32 v51, v51, v51
	v_max_f32_e32 v50, v50, v50
	v_max_f32_e32 v50, v50, v51
	s_and_b32 s4, s4, 0x3fffffc0
	v_add_f32_e32 v51, 0x7149f2ca, v50
	s_lshl_b32 s4, s4, 2
	v_mul_f32_e32 v51, 0x3db504f3, v51
	v_max_f32_e32 v50, 0xf149f2ca, v50
	s_add_i32 s14, s80, 0xff
	s_add_i32 s4, s4, 0
	v_cmp_ge_f32_e32 vcc, s86, v51
	v_sub_f32_e32 v51, 0xf149f2ca, v50
	s_lshr_b32 s24, s14, 6
	s_add_i32 s4, s4, 0x10000
	s_add_i32 s15, s13, 0xffffc01f
	v_mul_f32_e32 v51, 0x3e0293ee, v51
	v_exp_f32_e32 v51, v51
	s_cmp_eq_u64 vcc, exec
	s_cselect_b64 vcc, -1, 0
	v_cndmask_b32_e32 v178, v50, v216, vcc
	v_mul_f32_e32 v50, 0xbe0293ee, v178
	v_cndmask_b32_e64 v197, v51, 1.0, vcc
	v_mov_b32_e32 v51, v50
	v_fmamk_f32 v18, v18, 0x3e0293ee, v50
	v_fmamk_f32 v19, v19, 0x3e0293ee, v50
	v_fmamk_f32 v20, v20, 0x3e0293ee, v50
	v_fmamk_f32 v21, v21, 0x3e0293ee, v50
	v_fmamk_f32 v22, v22, 0x3e0293ee, v50
	v_fmamk_f32 v23, v23, 0x3e0293ee, v50
	v_fmamk_f32 v24, v24, 0x3e0293ee, v50
	v_fmamk_f32 v25, v25, 0x3e0293ee, v50
	v_fmamk_f32 v26, v26, 0x3e0293ee, v50
	v_fmamk_f32 v27, v27, 0x3e0293ee, v50
	v_fmamk_f32 v28, v28, 0x3e0293ee, v50
	v_fmamk_f32 v29, v29, 0x3e0293ee, v50
	v_fmamk_f32 v30, v30, 0x3e0293ee, v50
	v_fmamk_f32 v31, v31, 0x3e0293ee, v50
	v_fmamk_f32 v32, v32, 0x3e0293ee, v50
	v_fmac_f32_e32 v51, 0x3e0293ee, v33
	v_exp_f32_e32 v170, v18
	v_exp_f32_e32 v171, v19
	v_exp_f32_e32 v172, v20
	v_exp_f32_e32 v173, v21
	v_exp_f32_e32 v174, v22
	v_exp_f32_e32 v176, v23
	v_exp_f32_e32 v175, v24
	v_exp_f32_e32 v177, v25
	v_exp_f32_e32 v162, v26
	v_exp_f32_e32 v163, v27
	v_exp_f32_e32 v164, v28
	v_exp_f32_e32 v166, v29
	v_exp_f32_e32 v165, v30
	v_exp_f32_e32 v167, v31
	v_exp_f32_e32 v168, v32
	v_exp_f32_e32 v169, v51
	s_waitcnt vmcnt(0)
	s_waitcnt vmcnt(3)
	ds_write_b128 v209, v[34:37] offset:16384
	s_waitcnt vmcnt(1)
	ds_write_b128 v210, v[46:49] offset:16384
	ds_write_b128 v217, v[38:41] offset:49152
	s_waitcnt vmcnt(0)
	ds_write_b128 v217, v[42:45] offset:57344
	v_mov_b32_e32 v34, v195
	v_mov_b32_e32 v35, v195
	v_mov_b32_e32 v48, v195
	v_mov_b32_e32 v49, v195
	v_pk_fma_f32 v[118:119], v[16:17], s[50:51], v[50:51] op_sel_hi:[1,0,0]
	v_pk_fma_f32 v[122:123], v[14:15], s[50:51], v[50:51] op_sel_hi:[1,0,0]
	v_pk_fma_f32 v[128:129], v[12:13], s[50:51], v[50:51] op_sel_hi:[1,0,0]
	v_pk_fma_f32 v[114:115], v[10:11], s[50:51], v[50:51] op_sel_hi:[1,0,0]
	v_pk_fma_f32 v[116:117], v[8:9], s[50:51], v[50:51] op_sel_hi:[1,0,0]
	v_pk_fma_f32 v[120:121], v[6:7], s[50:51], v[50:51] op_sel_hi:[1,0,0]
	v_pk_fma_f32 v[124:125], v[4:5], s[50:51], v[50:51] op_sel_hi:[1,0,0]
	v_pk_fma_f32 v[126:127], v[2:3], s[50:51], v[50:51] op_sel_hi:[1,0,0]
	v_mov_b32_e32 v36, v195
	v_mov_b32_e32 v37, v195
	v_mov_b32_e32 v38, v195
	v_mov_b32_e32 v39, v195
	v_mov_b32_e32 v40, v195
	v_mov_b32_e32 v41, v195
	v_mov_b32_e32 v42, v195
	v_mov_b32_e32 v43, v195
	v_mov_b32_e32 v44, v195
	v_mov_b32_e32 v45, v195
	v_mov_b32_e32 v46, v195
	v_mov_b32_e32 v47, v195
	v_mov_b64_e32 v[64:65], v[48:49]
	v_mov_b64_e32 v[18:19], v[34:35]
	v_mov_b64_e32 v[2:3], v[34:35]
	s_mov_b32 s25, 2
	v_lshl_add_u32 v219, v199, 2, s4
	v_lshl_add_u32 v218, v200, 2, s4
	v_add_u32_e32 v222, s12, v201
	v_mov_b32_e32 v221, 0
	s_movk_i32 s26, 0xbf
	v_mov_b32_e32 v194, v203
	v_mov_b64_e32 v[62:63], v[46:47]
	v_mov_b64_e32 v[60:61], v[44:45]
	v_mov_b64_e32 v[58:59], v[42:43]
	v_mov_b64_e32 v[56:57], v[40:41]
	v_mov_b64_e32 v[54:55], v[38:39]
	v_mov_b64_e32 v[52:53], v[36:37]
	v_mov_b64_e32 v[50:51], v[34:35]
	v_mov_b64_e32 v[20:21], v[36:37]
	v_mov_b64_e32 v[22:23], v[38:39]
	v_mov_b64_e32 v[24:25], v[40:41]
	v_mov_b64_e32 v[26:27], v[42:43]
	v_mov_b64_e32 v[28:29], v[44:45]
	v_mov_b64_e32 v[30:31], v[46:47]
	v_mov_b64_e32 v[32:33], v[48:49]
	v_mov_b64_e32 v[4:5], v[36:37]
	v_mov_b64_e32 v[6:7], v[38:39]
	v_mov_b64_e32 v[8:9], v[40:41]
	v_mov_b64_e32 v[10:11], v[42:43]
	v_mov_b64_e32 v[12:13], v[44:45]
	v_mov_b64_e32 v[14:15], v[46:47]
	v_mov_b64_e32 v[16:17], v[48:49]
	s_waitcnt lgkmcnt(0)
	v_lshlrev_b32_e32 v255, 1, v194
	v_mov_b32_e32 v252, v178
	v_mul_f32_e32 v253, 0xbe0293ee, v178
	v_readfirstlane_b32 s52, v1
	s_nop 3
	s_and_b32 s52, s52, 0x3ff
	s_cmpk_ge_u32 s52, 0x100
	s_cbranch_scc0 .Lattn_prio_skip
	s_setprio 1
; __device__ __forceinline__ void finishSM(f32x16& p0, f32x16& p1, float alpha, float& l_reg, bf16x8& pa0, bf16x8& pa1, bf16x8& pa2, bf16x8& pa3) {
;     for (int r = 0; r < 16; ++r) p1[r] = __builtin_amdgcn_exp2f(p1[r]);
;     float ps = 0; for (int r = 0; r < 16; ++r) ps += p0[r]; for (int r = 0; r < 16; ++r) ps += p1[r];
;     { auto rr = __builtin_amdgcn_permlane32_swap(__float_as_uint(ps), __float_as_uint(ps), false, false);
;       ps = __uint_as_float(rr[0]) + __uint_as_float(rr[1]); }
;     l_reg = l_reg * alpha + ps;
;     ...
;     PK4(p0, 0, pa0); PK4(p0, 8, pa1); PK4(p1, 0, pa2); PK4(p1, 8, pa3);
;     ...
; }
; template <int KB, bool SK>
; __device__ __forceinline__ void qkt(f32x16& p0, f32x16& p1, const char* K_lds, int r32, int hi, const bf16x8* qr, bool act) {
;     if (SK && !act) { const float NEG = -__builtin_inff();
; #pragma unroll
;         for (int r = 0; r < 16; ++r) { p0[r] = NEG; p1[r] = NEG; } return; }
;     p0 = f32x16{}; p1 = f32x16{};
;     const char* kb[4];
; #pragma unroll
;     for (int dd = 0; dd < 4; ++dd) kb[dd] = K_lds + KB * SHM_K + KSWZ(r32, (dd * 16 + hi * 8) * 2);
; #pragma unroll
;     for (int d0 = 0; d0 < 8; ++d0) { const char* a = kb[d0 & 3] + (d0 >> 2) * 128;
;         bf16x8 b0 = *reinterpret_cast<const bf16x8*>(a);
;         bf16x8 b1 = *reinterpret_cast<const bf16x8*>(a + 32 * 256);
;         const bf16x8 qf = qr[d0];
;         p0 = __builtin_amdgcn_mfma_f32_32x32x16_bf16(b0, qf, p0, 0, 0, 0);
;         p1 = __builtin_amdgcn_mfma_f32_32x32x16_bf16(b1, qf, p1, 0, 0, 0); }
.Lattn_prio_skip:
.LBB0_1129:
	s_barrier
	ds_read_b128 v[180:183], v211 offset:49152
	ds_read_b128 v[184:187], v211 offset:57344
	ds_read_b128 v[188:191], v212 offset:49152
	ds_read_b128 v[228:231], v212 offset:57344
	ds_read_b128 v[232:235], v213 offset:49152
	ds_read_b128 v[236:239], v213 offset:57344
	ds_read_b128 v[240:243], v214 offset:49152
	ds_read_b128 v[244:247], v214 offset:57344
	v_exp_f32_e32 v126, v126
	v_exp_f32_e32 v127, v127
	v_exp_f32_e32 v124, v124
	v_exp_f32_e32 v125, v125
	v_exp_f32_e32 v120, v120
	v_exp_f32_e32 v121, v121
	s_add_i32 s4, s26, 0xffffff81
	s_sub_i32 s5, s26, 64
	s_waitcnt lgkmcnt(7)
	v_mfma_f32_32x32x16_bf16 v[86:101], v[180:183], v[158:161], 0
	ds_read_b128 v[180:183], v211 offset:49280
	v_exp_f32_e32 v116, v116
	v_exp_f32_e32 v117, v117
	v_exp_f32_e32 v114, v114
	v_exp_f32_e32 v115, v115
	v_exp_f32_e32 v128, v128
	s_waitcnt lgkmcnt(7)
	v_mfma_f32_32x32x16_bf16 v[70:85], v[184:187], v[158:161], 0
	ds_read_b128 v[184:187], v211 offset:57472
	v_exp_f32_e32 v129, v129
	v_exp_f32_e32 v122, v122
	v_exp_f32_e32 v123, v123
	v_exp_f32_e32 v118, v118
	v_exp_f32_e32 v119, v119
	s_waitcnt lgkmcnt(7)
	v_mfma_f32_32x32x16_bf16 v[86:101], v[188:191], v[154:157], v[86:101]
	ds_read_b128 v[188:191], v212 offset:49280
	v_add_f32_e32 v179, 0, v170
	v_add_f32_e32 v179, v171, v179
	v_add_f32_e32 v179, v172, v179
	v_add_f32_e32 v179, v173, v179
	v_add_f32_e32 v179, v174, v179
	s_waitcnt lgkmcnt(7)
	v_mfma_f32_32x32x16_bf16 v[70:85], v[228:231], v[154:157], v[70:85]
	ds_read_b128 v[228:231], v212 offset:57472
	v_add_f32_e32 v179, v176, v179
	v_add_f32_e32 v179, v175, v179
	v_add_f32_e32 v179, v177, v179
	v_add_f32_e32 v179, v162, v179
	v_add_f32_e32 v179, v163, v179
	s_waitcnt lgkmcnt(7)
	v_mfma_f32_32x32x16_bf16 v[86:101], v[232:235], v[150:153], v[86:101]
	ds_read_b128 v[232:235], v213 offset:49280
	v_add_f32_e32 v110, v164, v179
	v_add_f32_e32 v110, v166, v110
	v_add_f32_e32 v110, v165, v110
	v_add_f32_e32 v110, v167, v110
	s_waitcnt lgkmcnt(7)
	v_mfma_f32_32x32x16_bf16 v[70:85], v[236:239], v[150:153], v[70:85]
	ds_read_b128 v[236:239], v213 offset:57472
	v_add_f32_e32 v110, v168, v110
	v_add_f32_e32 v110, v169, v110
	v_add_f32_e32 v110, v126, v110
	v_add_f32_e32 v102, v127, v110
	s_waitcnt lgkmcnt(7)
	v_mfma_f32_32x32x16_bf16 v[86:101], v[240:243], v[134:137], v[86:101]
	ds_read_b128 v[240:243], v214 offset:49280
	v_add_f32_e32 v102, v124, v102
	v_add_f32_e32 v102, v125, v102
	v_add_f32_e32 v102, v120, v102
	v_add_f32_e32 v102, v121, v102
	s_waitcnt lgkmcnt(7)
	v_mfma_f32_32x32x16_bf16 v[70:85], v[244:247], v[134:137], v[70:85]
	ds_read_b128 v[244:247], v214 offset:57472
	v_add_f32_e32 v102, v116, v102
	v_add_f32_e32 v102, v117, v102
	v_add_f32_e32 v102, v114, v102
	v_add_f32_e32 v102, v115, v102
	s_waitcnt lgkmcnt(7)
	v_mfma_f32_32x32x16_bf16 v[86:101], v[180:183], v[138:141], v[86:101]
	v_add_f32_e32 v102, v128, v102
	v_add_f32_e32 v102, v129, v102
	v_add_f32_e32 v102, v122, v102
	v_add_f32_e32 v102, v123, v102
	s_waitcnt lgkmcnt(6)
	v_mfma_f32_32x32x16_bf16 v[70:85], v[184:187], v[138:141], v[70:85]
	v_add_f32_e32 v102, v118, v102
	v_add_f32_e32 v223, v119, v102
	v_mov_b32_e32 v224, v223
	s_nop 1
	v_permlane32_swap_b32_e32 v223, v224
	s_waitcnt lgkmcnt(5)
	v_mfma_f32_32x32x16_bf16 v[86:101], v[188:191], v[142:145], v[86:101]
	v_cvt_pk_bf16_f32 v102, v170, v171
	v_cvt_pk_bf16_f32 v103, v172, v173
	v_cvt_pk_bf16_f32 v104, v174, v176
	v_cvt_pk_bf16_f32 v105, v175, v177
	s_waitcnt lgkmcnt(4)
	v_mfma_f32_32x32x16_bf16 v[70:85], v[228:231], v[142:145], v[70:85]
	v_cvt_pk_bf16_f32 v66, v162, v163
	v_cvt_pk_bf16_f32 v67, v164, v166
	v_cvt_pk_bf16_f32 v68, v165, v167
	v_cvt_pk_bf16_f32 v69, v168, v169
	s_waitcnt lgkmcnt(3)
	v_mfma_f32_32x32x16_bf16 v[86:101], v[232:235], v[146:149], v[86:101]
	v_cvt_pk_bf16_f32 v106, v126, v127
	v_cvt_pk_bf16_f32 v107, v124, v125
	v_cvt_pk_bf16_f32 v108, v120, v121
	v_cvt_pk_bf16_f32 v109, v116, v117
	s_waitcnt lgkmcnt(2)
	v_mfma_f32_32x32x16_bf16 v[70:85], v[236:239], v[146:149], v[70:85]
	v_cvt_pk_bf16_f32 v110, v114, v115
	v_cvt_pk_bf16_f32 v111, v128, v129
	v_cvt_pk_bf16_f32 v112, v122, v123
	v_cvt_pk_bf16_f32 v113, v118, v119
	s_waitcnt lgkmcnt(1)
	v_mfma_f32_32x32x16_bf16 v[86:101], v[240:243], v[130:133], v[86:101]
	s_nop 1
	v_permlane32_swap_b32_e32 v102, v104
	v_permlane32_swap_b32_e32 v103, v105
	v_permlane32_swap_b32_e32 v66, v68
	v_permlane32_swap_b32_e32 v67, v69
	s_waitcnt lgkmcnt(0)
	v_mfma_f32_32x32x16_bf16 v[70:85], v[244:247], v[130:133], v[70:85]
	v_permlane32_swap_b32_e32 v106, v108
	v_permlane32_swap_b32_e32 v107, v109
	v_permlane32_swap_b32_e32 v110, v112
	v_permlane32_swap_b32_e32 v111, v113
	v_add_u32_e32 v114, 0x2000, v255
	global_load_dwordx4 v[162:165], v255, s[42:43]
	global_load_dwordx4 v[166:169], v114, s[42:43]
	global_load_dwordx4 v[170:173], v255, s[22:23]
	global_load_dwordx4 v[174:177], v114, s[22:23]
	s_cmp_le_i32 s5, s13
	s_cselect_b64 s[52:53], -1, 0
	s_cmp_gt_i32 s4, s15
	s_cselect_b64 s[4:5], -1, 0
	s_and_b64 s[4:5], s[52:53], s[4:5]
	s_and_b64 vcc, exec, s[4:5]
	ds_read_b64_tr_b16 v[114:115], v202 offset:0x0
	ds_read_b64_tr_b16 v[116:117], v202 offset:0x800
	ds_read_b64_tr_b16 v[118:119], v202 offset:0x1000
	ds_read_b64_tr_b16 v[120:121], v202 offset:0x1800
	ds_read_b64_tr_b16 v[122:123], v202 offset:0x2000
	ds_read_b64_tr_b16 v[124:125], v202 offset:0x2800
	ds_read_b64_tr_b16 v[126:127], v202 offset:0x3000
	ds_read_b64_tr_b16 v[128:129], v202 offset:0x3800
	ds_read_b64_tr_b16 v[182:183], v202 offset:0x200
	ds_read_b64_tr_b16 v[184:185], v202 offset:0xa00
	ds_read_b64_tr_b16 v[186:187], v202 offset:0x1200
	ds_read_b64_tr_b16 v[188:189], v202 offset:0x1a00
	ds_read_b64_tr_b16 v[190:191], v202 offset:0x2200
	ds_read_b64_tr_b16 v[192:193], v202 offset:0x2a00
	s_cbranch_vccnz .Lh1_nomask
; __device__ __forceinline__ void mask_tile(f32x16& p0, f32x16& p1, int dq, unsigned W) {
;     const float NEG = -__builtin_inff();
; #pragma unroll
;     for (int r = 0; r < 16; ++r) {
;         const int c = (r & 3) + 8 * (r >> 2);
;         if ((unsigned)(dq - c) >= W) p0[r] = NEG;
;         if ((unsigned)(dq - c - 32) >= W) p1[r] = NEG;
;     }
; }
	v_add_u32_e32 v226, s80, v222
	v_subrev_u32_e32 v240, 64, v226
	v_cmp_gt_u32_e32 vcc, s85, v240
	v_add_u32_e32 v240, 0xffffffa0, v226
	s_nop 0
	v_cndmask_b32_e32 v86, v215, v86, vcc
	v_cmp_gt_u32_e32 vcc, s85, v240
	v_add_u32_e32 v240, 0xffffffbf, v226
	s_nop 0
	v_cndmask_b32_e32 v70, v215, v70, vcc
	v_cmp_gt_u32_e32 vcc, s85, v240
	v_add_u32_e32 v240, 0xffffff9f, v226
	s_nop 0
	v_cndmask_b32_e32 v87, v215, v87, vcc
	v_cmp_gt_u32_e32 vcc, s85, v240
	v_add_u32_e32 v240, 0xffffffbe, v226
	s_nop 0
	v_cndmask_b32_e32 v71, v215, v71, vcc
	v_cmp_gt_u32_e32 vcc, s85, v240
	v_add_u32_e32 v240, 0xffffff9e, v226
	s_nop 0
	v_cndmask_b32_e32 v88, v215, v88, vcc
	v_cmp_gt_u32_e32 vcc, s85, v240
	v_add_u32_e32 v240, 0xffffffbd, v226
	s_nop 0
	v_cndmask_b32_e32 v72, v215, v72, vcc
	v_cmp_gt_u32_e32 vcc, s85, v240
	v_add_u32_e32 v240, 0xffffff9d, v226
	s_nop 0
	v_cndmask_b32_e32 v89, v215, v89, vcc
	v_cmp_gt_u32_e32 vcc, s85, v240
	v_add_u32_e32 v240, 0xffffffb8, v226
	s_nop 0
	v_cndmask_b32_e32 v73, v215, v73, vcc
	v_cmp_gt_u32_e32 vcc, s85, v240
	v_add_u32_e32 v240, 0xffffff98, v226
	s_nop 0
	v_cndmask_b32_e32 v90, v215, v90, vcc
	v_cmp_gt_u32_e32 vcc, s85, v240
	v_add_u32_e32 v240, 0xffffffb7, v226
	s_nop 0
	v_cndmask_b32_e32 v74, v215, v74, vcc
	v_cmp_gt_u32_e32 vcc, s85, v240
	v_add_u32_e32 v240, 0xffffff97, v226
	s_nop 0
	v_cndmask_b32_e32 v91, v215, v91, vcc
	v_cmp_gt_u32_e32 vcc, s85, v240
	v_add_u32_e32 v240, 0xffffffb6, v226
	s_nop 0
	v_cndmask_b32_e32 v75, v215, v75, vcc
	v_cmp_gt_u32_e32 vcc, s85, v240
	v_add_u32_e32 v240, 0xffffff96, v226
	s_nop 0
	v_cndmask_b32_e32 v92, v215, v92, vcc
	v_cmp_gt_u32_e32 vcc, s85, v240
	v_add_u32_e32 v240, 0xffffffb5, v226
	s_nop 0
	v_cndmask_b32_e32 v76, v215, v76, vcc
	v_cmp_gt_u32_e32 vcc, s85, v240
	v_add_u32_e32 v240, 0xffffff95, v226
	s_nop 0
	v_cndmask_b32_e32 v93, v215, v93, vcc
	v_cmp_gt_u32_e32 vcc, s85, v240
	v_add_u32_e32 v240, 0xffffffb0, v226
	s_nop 0
	v_cndmask_b32_e32 v77, v215, v77, vcc
	v_cmp_gt_u32_e32 vcc, s85, v240
	v_add_u32_e32 v240, 0xffffff90, v226
	s_nop 0
	v_cndmask_b32_e32 v94, v215, v94, vcc
	v_cmp_gt_u32_e32 vcc, s85, v240
	v_add_u32_e32 v240, 0xffffffaf, v226
	s_nop 0
	v_cndmask_b32_e32 v78, v215, v78, vcc
	v_cmp_gt_u32_e32 vcc, s85, v240
	v_add_u32_e32 v240, 0xffffff8f, v226
	s_nop 0
	v_cndmask_b32_e32 v95, v215, v95, vcc
	v_cmp_gt_u32_e32 vcc, s85, v240
	v_add_u32_e32 v240, 0xffffffae, v226
	s_nop 0
	v_cndmask_b32_e32 v79, v215, v79, vcc
	v_cmp_gt_u32_e32 vcc, s85, v240
	v_add_u32_e32 v240, 0xffffff8e, v226
	s_nop 0
	v_cndmask_b32_e32 v96, v215, v96, vcc
	v_cmp_gt_u32_e32 vcc, s85, v240
	v_add_u32_e32 v240, 0xffffffad, v226
	s_nop 0
	v_cndmask_b32_e32 v80, v215, v80, vcc
	v_cmp_gt_u32_e32 vcc, s85, v240
	v_add_u32_e32 v240, 0xffffff8d, v226
	s_nop 0
	v_cndmask_b32_e32 v97, v215, v97, vcc
	v_cmp_gt_u32_e32 vcc, s85, v240
	v_add_u32_e32 v240, 0xffffffa8, v226
	s_nop 0
	v_cndmask_b32_e32 v81, v215, v81, vcc
	v_cmp_gt_u32_e32 vcc, s85, v240
	v_add_u32_e32 v240, 0xffffff88, v226
	s_nop 0
	v_cndmask_b32_e32 v98, v215, v98, vcc
	v_cmp_gt_u32_e32 vcc, s85, v240
	v_add_u32_e32 v240, 0xffffffa7, v226
	s_nop 0
	v_cndmask_b32_e32 v82, v215, v82, vcc
	v_cmp_gt_u32_e32 vcc, s85, v240
	v_add_u32_e32 v240, 0xffffff87, v226
	s_nop 0
	v_cndmask_b32_e32 v99, v215, v99, vcc
	v_cmp_gt_u32_e32 vcc, s85, v240
	v_add_u32_e32 v240, 0xffffffa6, v226
	s_nop 0
	v_cndmask_b32_e32 v83, v215, v83, vcc
	v_cmp_gt_u32_e32 vcc, s85, v240
	v_add_u32_e32 v240, 0xffffff86, v226
	s_nop 0
	v_cndmask_b32_e32 v100, v215, v100, vcc
	v_cmp_gt_u32_e32 vcc, s85, v240
	v_add_u32_e32 v240, 0xffffffa5, v226
	s_nop 0
	v_cndmask_b32_e32 v84, v215, v84, vcc
	v_cmp_gt_u32_e32 vcc, s85, v240
	v_add_u32_e32 v240, 0xffffff85, v226
	s_nop 0
	v_cndmask_b32_e32 v101, v215, v101, vcc
	v_cmp_gt_u32_e32 vcc, s85, v240
	s_nop 1
	v_cndmask_b32_e32 v85, v215, v85, vcc

; __device__ __forceinline__ void partialSM(f32x16& p0, f32x16& p1, float& m_reg, float& mn, float& alpha) {
;     ...
;     for (int r = 0; r < 16; ++r) p0[r] = __builtin_amdgcn_exp2f(p0[r]);
; template <class TIn, class TOut>
; __device__ __forceinline__ void causal_swa_block(const BlockRef<TIn, TOut>& cur, const BlockRef<TIn, TOut>& nxt, int skv, int W, char* lds, Seam<TIn>& S) {
;     ...
;     for (int t = 1; t + 1 < NT; t += 2) {
;         HALF_STEP(pB0, pB1, mnB, alB, pA0, pA1, alA, t, 1, 0, 0);
;         HALF_STEP(pA0, pA1, mnA, alA, pB0, pB1, alB, t + 1, 0, 1, 1);
;     }
.Lh2_noresc:
	v_exp_f32_e32 v170, v68
	v_exp_f32_e32 v171, v69
	v_exp_f32_e32 v172, v70
	v_exp_f32_e32 v173, v71
	v_exp_f32_e32 v174, v79
	v_exp_f32_e32 v176, v80
	v_exp_f32_e32 v175, v72
	v_exp_f32_e32 v177, v73
	v_exp_f32_e32 v162, v81
	v_exp_f32_e32 v163, v82
	v_exp_f32_e32 v164, v74
	v_exp_f32_e32 v166, v75
	v_exp_f32_e32 v165, v76
	v_exp_f32_e32 v167, v77
	v_exp_f32_e32 v168, v83
	v_exp_f32_e32 v169, v78
	s_cmp_gt_u32 s25, s24
	s_waitcnt lgkmcnt(0)
	s_cbranch_scc1 .Lattn_exit
	v_mov_b32_e32 v197, v254
	s_branch .LBB0_1129

; #define SBAR() __builtin_amdgcn_sched_barrier(0)
; #define ACT(t) (KBASE(t) <= qlo + QBLK - 1 && KBASE(t) + KVBLK - 1 >= qlo - W + 1)
; template <class TIn, class TOut>
; __device__ __forceinline__ void causal_swa_block(const BlockRef<TIn, TOut>& cur, const BlockRef<TIn, TOut>& nxt, int skv, int W, char* lds, Seam<TIn>& S) {
;     ...
;     for (int t = 1; t + 1 < NT; t += 2) {
;         HALF_STEP(pB0, pB1, mnB, alB, pA0, pA1, alA, t, 1, 0, 0);
;         HALF_STEP(pA0, pA1, mnA, alA, pB0, pB1, alB, t + 1, 0, 1, 1);
;     }
;     const bool even = (NT & 1) == 0;
;     if (even) { SBAR(); qkt<1, SK>(pB0, pB1, K_lds, r32, hi, S.qr, ACT(NT - 1)); SBAR(); }
.Lattn_exit:
	s_barrier
	v_mov_b32_e32 v178, v252
	v_mov_b32_e32 v179, v254
	s_setprio 0
